# attention tail: all-rows-zero-reference test cached in an SGPR flag (updated only on the slow rescale path)
# speedup vs baseline: 1.0060x; 1.0007x over previous
; #define LAS __attribute__((address_space(3)))
; #define SBAR() __builtin_amdgcn_sched_barrier(0)
; __device__ __forceinline__ int v_rd_base(int lane) { return ((lane & 3) << 3) | (((lane >> 2) & 3) << 6) | (((lane >> 4) & 1) << 5) | (((lane >> 5) & 1) << 8); }
; #define WAIT_BAR() asm volatile("s_waitcnt vmcnt(0) lgkmcnt(0)\n\ts_barrier" ::: "memory")
; __device__ __forceinline__ void attn_unit(const bf16_t* __restrict__ Qb, const bf16_t* __restrict__ Kn, const bf16_t* __restrict__ Vh, const bf16_t* __restrict__ Kr,
;                                           bf16_t* __restrict__ Ob, int seq, char* lds, int wv_) { LAUNDER_IDS;
;     const int tid = tidx_, wid = __builtin_amdgcn_readfirstlane(tid >> 6), lane = tid & 63, r32 = lane & 31, hi = lane >> 5;
;     LAS unsigned char* lds3 = (LAS unsigned char*)lds;
;     float* ws = (float*)(lds + OFF_WS) + wid * 64; float* li_l = ws; float* al_l = ws + 32;
;     float m_reg = 0.f, l_reg = 0; f32x16 o[4] = {}; bf16x8 qr[12];
;     const bf16_t* Qw = Qb + (long)(wid * QBLK + r32) * LDQ + hi * 8;
; #pragma unroll
;     for (int d0 = 0; d0 < 12; ++d0) qr[d0] = *reinterpret_cast<const bf16x8*>(Qw + d0 * 16);
;     unsigned gkn[2], gv[2], gkr;
; #pragma unroll
;     for (int i = 0; i < 2; ++i) { const int c = wid * 2 + i; const int row = c * 4 + (lane >> 4), slot = lane & 15; gkn[i] = (unsigned)(row * (LDKV * 2) + ((slot ^ (row & 15)) << 4));
;         const int st = c * 2 + (lane >> 5), kk = (st >> 2) * 8 + ((lane & 31) >> 2), k = (kk & ~0xC) | ((kk & 4) << 1) | ((kk & 8) >> 1), col = (st & 3) * 32 + (lane & 3) * 8; gv[i] = (unsigned)(k * (LDKV * 2) + col * 2); }
;     { const int row = wid * 8 + (lane >> 3), slot = lane & 7; gkr = (unsigned)(row * 128 + ((slot ^ ((row >> 1) & 7)) << 4)); }
;     const int vb0 = (int)(uintptr_t)(lds + OFF_V) + v_rd_base(lane);
;     ...
;     f32x16 pA0, pA1, pB0, pB1; float mnA, mnB, alA, alB; bf16x8 pa0, pa1, pa2, pa3; const int NT = seq / KVBLK;
;     DMA(0, 0); DMA(1, 1); WAIT_BAR();
;     qkt(pA0, pA1, lds + OFF_K, qr, r32, hi); __builtin_amdgcn_s_setprio(0); partialSM<true>(pA0, pA1, m_reg, mnA, alA);
;     int s_prev = 0, s_cur = 1, s_next = 2;
;     ...
;     for (int j = 1; j + 1 < NT; j += 2) {
;         DMA(j + 1, s_next); SBAR();
;         qkt(pB0, pB1, lds + OFF_K + s_cur * SLOT_K, qr, r32, hi);
.LBB0_215:
	s_and_b32 s5, s5, 0x3fffffc0
	s_lshl_b32 s5, s5, 2
	s_add_i32 s5, s5, 0
	s_add_i32 s5, s5, 0x1e000
	v_exp_f32_e32 v247, v0
	v_lshlrev_b32_e32 v0, 7, v24
	s_cmp_lg_u32 0, -1
	v_add3_u32 v174, s8, v0, v25
	v_add3_u32 v0, v17, v18, s14
	v_and_b32_e32 v22, 63, v22
	s_cselect_b32 s16, 0, 0
	v_lshl_or_b32 v0, v0, 13, v23
	s_lshl_b32 s13, s13, 16
	v_lshlrev_b32_e32 v27, 4, v22
	v_exp_f32_e32 v249, v1
	v_exp_f32_e32 v245, v2
	v_add_u32_e32 v0, v0, v20
	v_mov_b32_e32 v1, v161
	v_lshl_or_b32 v2, v16, 13, s13
	v_lshlrev_b32_e32 v26, 3, v22
	v_and_b32_e32 v27, 0xc0, v27
	v_lshlrev_b32_e32 v28, 1, v22
	v_exp_f32_e32 v248, v3
	v_exp_f32_e32 v244, v4
	v_exp_f32_e32 v246, v5
	v_exp_f32_e32 v242, v6
	v_exp_f32_e32 v243, v7
	v_exp_f32_e32 v239, v8
	v_exp_f32_e32 v241, v9
	v_exp_f32_e32 v238, v10
	v_exp_f32_e32 v240, v11
	v_exp_f32_e32 v235, v12
	v_exp_f32_e32 v237, v13
	v_exp_f32_e32 v234, v14
	v_exp_f32_e32 v236, v15
	v_lshl_add_u64 v[176:177], s[0:1], 0, v[0:1]
	v_or_b32_e32 v0, v2, v19
	s_mov_b32 s13, 0x8000
	v_and_or_b32 v27, v26, 24, v27
	v_and_b32_e32 v28, 32, v28
	v_and_b32_e32 v26, 0x100, v26
	v_lshl_add_u64 v[178:179], s[0:1], 0, v[0:1]
	v_or3_b32 v0, v2, v21, s13
	v_mov_b32_e32 v14, v161
	v_mov_b32_e32 v15, v161
	v_or3_b32 v204, v27, v28, v26
	s_add_i32 s16, s16, 0x12000
	v_cmp_gt_u32_e64 s[38:39], 32, v22
	v_lshl_add_u64 v[180:181], s[0:1], 0, v[0:1]
	v_mov_b32_e32 v0, v161
	v_mov_b32_e32 v2, v161
	v_mov_b32_e32 v3, v161
	v_mov_b32_e32 v4, v161
	v_mov_b32_e32 v5, v161
	v_mov_b32_e32 v6, v161
	v_mov_b32_e32 v7, v161
	v_mov_b32_e32 v8, v161
	v_mov_b32_e32 v9, v161
	v_mov_b32_e32 v10, v161
	v_mov_b32_e32 v11, v161
	v_mov_b32_e32 v12, v161
	v_mov_b32_e32 v13, v161
	v_mov_b64_e32 v[62:63], v[14:15]
	v_mov_b64_e32 v[46:47], v[14:15]
	v_mov_b64_e32 v[30:31], v[14:15]
	s_mov_b32 s9, 2
	s_mov_b32 s10, 1
	s_mov_b32 s11, -1
	s_mov_b32 s15, 0
	v_add_u32_e32 v205, s16, v204
	v_lshl_add_u32 v202, v183, 2, s5
	v_mov_b32_e32 v175, v161
	v_mov_b32_e32 v203, 0
	v_mov_b32_e32 v230, 1.0
	v_mov_b64_e32 v[60:61], v[12:13]
	v_mov_b64_e32 v[58:59], v[10:11]
	v_mov_b64_e32 v[56:57], v[8:9]
	v_mov_b64_e32 v[54:55], v[6:7]
	v_mov_b64_e32 v[52:53], v[4:5]
	v_mov_b64_e32 v[50:51], v[2:3]
	v_mov_b64_e32 v[48:49], v[0:1]
	v_mov_b64_e32 v[44:45], v[12:13]
	v_mov_b64_e32 v[42:43], v[10:11]
	v_mov_b64_e32 v[40:41], v[8:9]
	v_mov_b64_e32 v[38:39], v[6:7]
	v_mov_b64_e32 v[36:37], v[4:5]
	v_mov_b64_e32 v[34:35], v[2:3]
	v_mov_b64_e32 v[32:33], v[0:1]
	v_mov_b64_e32 v[28:29], v[12:13]
	v_mov_b64_e32 v[26:27], v[10:11]
	v_mov_b64_e32 v[24:25], v[8:9]
	v_mov_b64_e32 v[22:23], v[6:7]
	v_mov_b64_e32 v[20:21], v[4:5]
	v_mov_b64_e32 v[18:19], v[2:3]
	v_mov_b64_e32 v[16:17], v[0:1]
	v_cmp_eq_f32_e64 s[0:1], 0, v182
	s_cmp_eq_u64 s[0:1], exec
	s_cselect_b32 s19, 1, 0
.LBB0_216:
	s_mul_i32 s0, s9, 0x6000
	s_add_i32 s14, s0, 0
	s_lshl_b32 s13, s9, 14
	s_add_i32 s16, s14, s6
	s_add_i32 s17, s7, s13
	s_add_i32 s18, s14, s8
	s_mov_b32 s13, s10
	s_mov_b32 s10, s15
	s_mul_i32 s0, s13, 0x6000
	s_add_i32 s0, s0, 0
	s_setprio 1
	v_add_u32_e32 v84, s0, v207
	ds_read_b128 v[80:83], v84
	ds_read_b128 v[84:87], v84 offset:8192
	v_add_u32_e32 v168, s0, v210
	ds_read_b128 v[196:199], v168
	ds_read_b128 v[168:171], v168 offset:8192
	v_add_u32_e32 v184, s0, v218
	s_waitcnt lgkmcnt(0)
	v_mfma_f32_32x32x16_bf16 v[96:111], v[80:83], v[156:159], 0
	v_mfma_f32_32x32x16_bf16 v[80:95], v[84:87], v[156:159], 0
	v_mfma_f32_32x32x16_bf16 v[96:111], v[196:199], v[152:155], v[96:111]
	v_mfma_f32_32x32x16_bf16 v[80:95], v[168:171], v[152:155], v[80:95]
	ds_read_b128 v[168:171], v184
	ds_read_b128 v[196:199], v184 offset:8192
	v_add_u32_e32 v184, s0, v221
	s_mov_b32 m0, s16
	s_add_u32 s100, s72, 0x26500000
	s_addc_u32 s101, s73, 0
	global_load_lds_dwordx4 v178, s[100:101]
	s_waitcnt lgkmcnt(0)
	v_mfma_f32_32x32x16_bf16 v[96:111], v[168:171], v[148:151], v[96:111]
	v_mfma_f32_32x32x16_bf16 v[80:95], v[196:199], v[148:151], v[80:95]
	ds_read_b128 v[168:171], v184
	ds_read_b128 v[196:199], v184 offset:8192
	v_add_u32_e32 v184, s0, v222
	s_waitcnt lgkmcnt(0)
	v_mfma_f32_32x32x16_bf16 v[96:111], v[168:171], v[144:147], v[96:111]
	v_mfma_f32_32x32x16_bf16 v[80:95], v[196:199], v[144:147], v[80:95]
	ds_read_b128 v[168:171], v184
	ds_read_b128 v[196:199], v184 offset:8192
	v_add_u32_e32 v184, s0, v223
	s_add_i32 m0, s16, 0x400
	s_nop 0
	global_load_lds_dwordx4 v180, s[100:101]
	s_waitcnt lgkmcnt(0)
	v_mfma_f32_32x32x16_bf16 v[96:111], v[168:171], v[140:143], v[96:111]
	v_mfma_f32_32x32x16_bf16 v[80:95], v[196:199], v[140:143], v[80:95]
	ds_read_b128 v[168:171], v184
	ds_read_b128 v[196:199], v184 offset:8192
	v_add_u32_e32 v184, s0, v224
	v_exp_f32_e32 v233, v73
	s_waitcnt lgkmcnt(0)
	v_mfma_f32_32x32x16_bf16 v[96:111], v[168:171], v[136:139], v[96:111]
	v_mfma_f32_32x32x16_bf16 v[80:95], v[196:199], v[136:139], v[80:95]
	ds_read_b128 v[168:171], v184
	ds_read_b128 v[196:199], v184 offset:8192
	v_add_u32_e32 v184, s0, v225
	s_mov_b32 m0, s17
	s_add_u32 s100, s72, 0x26500100
	s_addc_u32 s101, s73, 0
	global_load_lds_dwordx4 v176, s[100:101]
	v_exp_f32_e32 v250, v74
	s_waitcnt lgkmcnt(0)
	v_mfma_f32_32x32x16_bf16 v[96:111], v[168:171], v[132:135], v[96:111]
	v_mfma_f32_32x32x16_bf16 v[80:95], v[196:199], v[132:135], v[80:95]
	ds_read_b128 v[168:171], v184
	ds_read_b128 v[196:199], v184 offset:8192
	v_add_u32_e32 v184, s0, v226
	v_exp_f32_e32 v200, v75
	s_waitcnt lgkmcnt(0)
	v_mfma_f32_32x32x16_bf16 v[96:111], v[168:171], v[128:131], v[96:111]
	v_mfma_f32_32x32x16_bf16 v[80:95], v[196:199], v[128:131], v[80:95]
	ds_read_b128 v[168:171], v184 offset:16384
	ds_read_b128 v[196:199], v184 offset:20480
	v_add_u32_e32 v184, s0, v227
	s_add_i32 m0, s17, 0x400
	s_add_u32 s100, s72, 0x26500180
	s_addc_u32 s101, s73, 0
	global_load_lds_dwordx4 v176, s[100:101]
	v_exp_f32_e32 v195, v76
	s_waitcnt lgkmcnt(0)
; __device__ __forceinline__ void finishSM(f32x16& p0, f32x16& p1, float alpha, float& l_reg, bf16x8& pa0, bf16x8& pa1, bf16x8& pa2, bf16x8& pa3) {
; #pragma unroll
;     for (int r = 0; r < 16; ++r) p1[r] = __builtin_amdgcn_exp2f(p1[r]);
;     float ps = 0;
; #pragma unroll
;     for (int r = 0; r < 16; ++r) ps += p0[r];
; #pragma unroll
;     for (int r = 0; r < 16; ++r) ps += p1[r];
;     { auto rr = __builtin_amdgcn_permlane32_swap(__float_as_uint(ps), __float_as_uint(ps), false, false);
;       ps = __uint_as_float(rr[0]) + __uint_as_float(rr[1]); }
;     l_reg = l_reg * alpha + ps;
;     ...
;     PK4(p0, 0, pa0); PK4(p0, 8, pa1); PK4(p1, 0, pa2); PK4(p1, 8, pa3);
;     ...
; }
; __device__ __forceinline__ void qkt(f32x16& p0, f32x16& p1, const char* Kn, const bf16x8* qr, int r32, int hi) {
;     const char* Kr = Kn + KR_OFF;
;     p0 = f32x16{}; p1 = f32x16{};
;     __builtin_amdgcn_s_setprio(1);
; #pragma unroll
;     for (int d0 = 0; d0 < 8; ++d0) { const int cb = (d0 * 16 + hi * 8) * 2;
;         const bf16x8 b0 = *reinterpret_cast<const bf16x8*>(Kn + KNSWZ(r32, cb));
;         const bf16x8 b1 = *reinterpret_cast<const bf16x8*>(Kn + KNSWZ(32 + r32, cb));
;         p0 = __builtin_amdgcn_mfma_f32_32x32x16_bf16(b0, qr[d0], p0, 0, 0, 0);
;         p1 = __builtin_amdgcn_mfma_f32_32x32x16_bf16(b1, qr[d0], p1, 0, 0, 0); }
; #pragma unroll
;     for (int d0 = 0; d0 < 4; ++d0) { const int cb = (d0 * 16 + hi * 8) * 2;
;         const bf16x8 b0 = *reinterpret_cast<const bf16x8*>(Kr + KRSWZ(r32, cb));
;         const bf16x8 b1 = *reinterpret_cast<const bf16x8*>(Kr + KRSWZ(32 + r32, cb));
;         p0 = __builtin_amdgcn_mfma_f32_32x32x16_bf16(b0, qr[8 + d0], p0, 0, 0, 0);
;         p1 = __builtin_amdgcn_mfma_f32_32x32x16_bf16(b1, qr[8 + d0], p1, 0, 0, 0); }
; }
; __device__ __forceinline__ int v_st(int k, int c) { const int kk = (k & ~0xC) | ((k & 4) << 1) | ((k & 8) >> 1); return ((kk >> 3) * 4 + (c >> 5)) * 512 + ((kk & 7) * 32 + (c & 31)) * 2; }
; __device__ __forceinline__ int v_rd_base(int lane) { return ((lane & 3) << 3) | (((lane >> 2) & 3) << 6) | (((lane >> 4) & 1) << 5) | (((lane >> 5) & 1) << 8); }
; template <int OFF> __device__ __forceinline__ s16x4 tr_read(int vb) {
;     s16x4 r; asm volatile("ds_read_b64_tr_b16 %0, %1 offset:%2" : "=&v"(r) : "v"(vb), "i"(OFF) : "memory"); return r;
; }
	v_mfma_f32_32x32x16_bf16 v[96:111], v[168:171], v[124:127], v[96:111]
	v_mfma_f32_32x32x16_bf16 v[80:95], v[196:199], v[124:127], v[80:95]
	ds_read_b128 v[168:171], v184 offset:16384
	ds_read_b128 v[196:199], v184 offset:20480
	v_add_u32_e32 v184, s0, v228
	v_exp_f32_e32 v172, v77
	s_waitcnt lgkmcnt(0)
	v_mfma_f32_32x32x16_bf16 v[96:111], v[168:171], v[120:123], v[96:111]
	v_mfma_f32_32x32x16_bf16 v[80:95], v[196:199], v[120:123], v[80:95]
	ds_read_b128 v[168:171], v184 offset:16384
	ds_read_b128 v[196:199], v184 offset:20480
	v_add_u32_e32 v184, s0, v229
	s_add_i32 m0, s18, 0x4000
	s_add_u32 s100, s72, 0x21204000
	s_addc_u32 s101, s73, 0
	global_load_lds_dwordx4 v174, s[100:101]
	v_exp_f32_e32 v173, v78
	s_waitcnt lgkmcnt(0)
	v_mfma_f32_32x32x16_bf16 v[96:111], v[168:171], v[116:119], v[96:111]
	v_mfma_f32_32x32x16_bf16 v[80:95], v[196:199], v[116:119], v[80:95]
	ds_read_b128 v[168:171], v184 offset:16384
	ds_read_b128 v[196:199], v184 offset:20480
	v_exp_f32_e32 v184, v68
	v_exp_f32_e32 v79, v79
	s_waitcnt lgkmcnt(0)
	v_mfma_f32_32x32x16_bf16 v[96:111], v[168:171], v[112:115], v[96:111]
	v_exp_f32_e32 v168, v64
	v_add_f32_e32 v64, 0, v247
	v_add_f32_e32 v64, v249, v64
	v_add_f32_e32 v64, v245, v64
	v_add_f32_e32 v64, v248, v64
	v_add_f32_e32 v64, v244, v64
	v_add_f32_e32 v64, v246, v64
	v_add_f32_e32 v64, v242, v64
	v_add_f32_e32 v64, v243, v64
	v_add_f32_e32 v64, v239, v64
	v_add_f32_e32 v64, v241, v64
	v_add_f32_e32 v64, v238, v64
	v_add_f32_e32 v64, v240, v64
	v_add_f32_e32 v64, v235, v64
	v_exp_f32_e32 v169, v65
	v_add_f32_e32 v64, v237, v64
	v_exp_f32_e32 v170, v66
	v_add_f32_e32 v64, v234, v64
	v_exp_f32_e32 v171, v67
	v_add_f32_e32 v64, v236, v64
	v_add_f32_e32 v64, v168, v64
	v_mfma_f32_32x32x16_bf16 v[80:95], v[196:199], v[112:115], v[80:95]
	v_exp_f32_e32 v196, v69
	v_add_f32_e32 v64, v169, v64
	v_exp_f32_e32 v197, v70
	v_add_f32_e32 v64, v170, v64
	v_exp_f32_e32 v198, v71
	v_add_f32_e32 v64, v171, v64
	v_exp_f32_e32 v199, v72
	v_add_f32_e32 v64, v184, v64
	v_add_f32_e32 v64, v196, v64
	v_add_f32_e32 v64, v197, v64
	v_add_f32_e32 v64, v198, v64
	v_add_f32_e32 v64, v199, v64
	v_add_f32_e32 v64, v233, v64
	v_add_f32_e32 v64, v250, v64
	v_add_f32_e32 v64, v200, v64
	v_add_f32_e32 v64, v195, v64
	v_add_f32_e32 v64, v172, v64
	v_add_f32_e32 v64, v173, v64
	v_add_f32_e32 v231, v79, v64
	v_mov_b32_e32 v232, v231
	v_cvt_pk_bf16_f32 v64, v247, v249
	v_cvt_pk_bf16_f32 v65, v245, v248
	v_cvt_pk_bf16_f32 v66, v244, v246
	s_nop 1
	v_permlane32_swap_b32_e32 v231, v232
	v_cvt_pk_bf16_f32 v67, v242, v243
	v_permlane32_swap_b32_e32 v64, v66
	v_cvt_pk_bf16_f32 v68, v239, v241
	v_cvt_pk_bf16_f32 v69, v238, v240
	v_cvt_pk_bf16_f32 v70, v235, v237
	v_cvt_pk_bf16_f32 v71, v234, v236
	v_cvt_pk_bf16_f32 v72, v168, v169
	v_cvt_pk_bf16_f32 v73, v170, v171
	v_cvt_pk_bf16_f32 v74, v184, v196
	v_cvt_pk_bf16_f32 v75, v197, v198
	v_cvt_pk_bf16_f32 v76, v199, v233
	v_cvt_pk_bf16_f32 v77, v250, v200
	v_cvt_pk_bf16_f32 v78, v195, v172
	v_cvt_pk_bf16_f32 v79, v173, v79
	v_permlane32_swap_b32_e32 v65, v67
	v_permlane32_swap_b32_e32 v68, v70
	v_permlane32_swap_b32_e32 v69, v71
	v_permlane32_swap_b32_e32 v72, v74
	v_permlane32_swap_b32_e32 v73, v75
	v_permlane32_swap_b32_e32 v76, v78
	v_permlane32_swap_b32_e32 v77, v79
	s_setprio 0
	s_lshl_b32 s15, s15, 14
	v_add_u32_e32 v172, s15, v205
	ds_read_b64_tr_b16 v[168:169], v172 offset:0
	ds_read_b64_tr_b16 v[170:171], v172 offset:0x800
	ds_read_b64_tr_b16 v[196:197], v172 offset:0x1000
	ds_read_b64_tr_b16 v[198:199], v172 offset:0x1800
	ds_read_b64_tr_b16 v[234:235], v172 offset:0x2000
	ds_read_b64_tr_b16 v[236:237], v172 offset:0x2800
	ds_read_b64_tr_b16 v[238:239], v172 offset:0x3000
	ds_read_b64_tr_b16 v[240:241], v172 offset:0x3800
	s_waitcnt lgkmcnt(0)
	s_nop 0
	v_mfma_f32_32x32x16_bf16 v[0:15], v[64:67], v[168:171], v[0:15]
	ds_read_b64_tr_b16 v[168:169], v172 offset:0x200
	ds_read_b64_tr_b16 v[170:171], v172 offset:0xa00
	v_mfma_f32_32x32x16_bf16 v[0:15], v[68:71], v[196:199], v[0:15]
	ds_read_b64_tr_b16 v[196:197], v172 offset:0x1200
	ds_read_b64_tr_b16 v[198:199], v172 offset:0x1a00
	v_mfma_f32_32x32x16_bf16 v[0:15], v[72:75], v[234:237], v[0:15]
	ds_read_b64_tr_b16 v[234:235], v172 offset:0x2200
	ds_read_b64_tr_b16 v[236:237], v172 offset:0x2a00
	v_mfma_f32_32x32x16_bf16 v[0:15], v[76:79], v[238:241], v[0:15]
	ds_read_b64_tr_b16 v[238:239], v172 offset:0x3200
	ds_read_b64_tr_b16 v[240:241], v172 offset:0x3a00
	s_waitcnt lgkmcnt(0)
	v_mfma_f32_32x32x16_bf16 v[48:63], v[64:67], v[168:171], v[48:63]
	ds_read_b64_tr_b16 v[168:169], v172 offset:0x400
	ds_read_b64_tr_b16 v[170:171], v172 offset:0xc00
	v_mfma_f32_32x32x16_bf16 v[48:63], v[68:71], v[196:199], v[48:63]
	ds_read_b64_tr_b16 v[196:197], v172 offset:0x1400
	ds_read_b64_tr_b16 v[198:199], v172 offset:0x1c00
	v_mfma_f32_32x32x16_bf16 v[48:63], v[72:75], v[234:237], v[48:63]
	ds_read_b64_tr_b16 v[234:235], v172 offset:0x2400
	ds_read_b64_tr_b16 v[236:237], v172 offset:0x2c00
	v_mfma_f32_32x32x16_bf16 v[48:63], v[76:79], v[238:241], v[48:63]
	ds_read_b64_tr_b16 v[238:239], v172 offset:0x3400
	ds_read_b64_tr_b16 v[240:241], v172 offset:0x3c00
	s_waitcnt lgkmcnt(0)
	v_mfma_f32_32x32x16_bf16 v[32:47], v[64:67], v[168:171], v[32:47]
	ds_read_b64_tr_b16 v[168:169], v172 offset:0x600
	ds_read_b64_tr_b16 v[170:171], v172 offset:0xe00
	v_mfma_f32_32x32x16_bf16 v[32:47], v[68:71], v[196:199], v[32:47]
	ds_read_b64_tr_b16 v[196:197], v172 offset:0x1600
	ds_read_b64_tr_b16 v[198:199], v172 offset:0x1e00
	v_mfma_f32_32x32x16_bf16 v[32:47], v[72:75], v[234:237], v[32:47]
	ds_read_b64_tr_b16 v[234:235], v172 offset:0x2600
	ds_read_b64_tr_b16 v[236:237], v172 offset:0x2e00
	v_mfma_f32_32x32x16_bf16 v[32:47], v[76:79], v[238:241], v[32:47]
	ds_read_b64_tr_b16 v[238:239], v172 offset:0x3600
	ds_read_b64_tr_b16 v[240:241], v172 offset:0x3e00
	s_waitcnt lgkmcnt(0)
	v_mfma_f32_32x32x16_bf16 v[16:31], v[64:67], v[168:171], v[16:31]
	v_max_f32_e32 v64, v97, v97
	v_max_f32_e32 v65, v96, v96
	v_max_f32_e32 v64, v65, v64
	v_max3_f32 v64, v64, v98, v99
	v_max3_f32 v64, v64, v100, v101
	v_max3_f32 v64, v64, v102, v103
	v_max3_f32 v64, v64, v104, v105
	v_mfma_f32_32x32x16_bf16 v[16:31], v[68:71], v[196:199], v[16:31]
	v_max3_f32 v64, v64, v106, v107
	v_max3_f32 v64, v64, v108, v109
	v_max3_f32 v64, v64, v110, v111
	v_max3_f32 v64, v64, v80, v81
	v_max3_f32 v64, v64, v82, v83
	v_max3_f32 v64, v64, v84, v85
	v_max3_f32 v64, v64, v86, v87
	v_mfma_f32_32x32x16_bf16 v[16:31], v[72:75], v[234:237], v[16:31]
	v_max3_f32 v64, v64, v88, v89
	v_max3_f32 v64, v64, v90, v91
	v_max3_f32 v64, v64, v92, v93
	v_max3_f32 v64, v64, v94, v95
	v_mov_b32_e32 v65, v64
	s_nop 1
	v_permlane32_swap_b32_e32 v64, v65
	v_max_f32_e32 v65, v65, v65
	v_max_f32_e32 v64, v64, v64
	v_mfma_f32_32x32x16_bf16 v[16:31], v[76:79], v[238:241], v[16:31]
	v_max_f32_e32 v64, v64, v65
	v_sub_f32_e32 v65, v64, v182
	s_mov_b32 s0, 0x41300000
	v_cmp_ge_f32_e32 vcc, s0, v65
	s_cmp_eq_u64 vcc, exec
	s_cbranch_scc0 .Latt_slow1
; template <bool FIRST>
; __device__ __forceinline__ void partialSM(f32x16& p0, f32x16& p1, float& m_reg, float& mn, float& alpha) {
;     ...
;     else if (__builtin_expect(__all(pmax - m_reg <= THRL), 1)) { mn = m_reg; alpha = 1.f; }
;     else { mn = fmaxf(m_reg, pmax); alpha = __builtin_amdgcn_exp2f(m_reg - mn); m_reg = mn; }
;     if (!__builtin_expect(__all(mn == 0.f), 1)) {
; #pragma unroll
;         for (int r = 0; r < 16; ++r) p0[r] = p0[r] - mn;
; #pragma unroll
;         for (int r = 0; r < 16; ++r) p1[r] = p1[r] - mn; }
; #pragma unroll
;     for (int r = 0; r < 16; ++r) p0[r] = __builtin_amdgcn_exp2f(p0[r]);
; __device__ __forceinline__ void qkt(f32x16& p0, f32x16& p1, const char* Kn, const bf16x8* qr, int r32, int hi) {
;     const char* Kr = Kn + KR_OFF;
;     p0 = f32x16{}; p1 = f32x16{};
;     __builtin_amdgcn_s_setprio(1);
; #pragma unroll
;     for (int d0 = 0; d0 < 8; ++d0) { const int cb = (d0 * 16 + hi * 8) * 2;
;         const bf16x8 b0 = *reinterpret_cast<const bf16x8*>(Kn + KNSWZ(r32, cb));
;         const bf16x8 b1 = *reinterpret_cast<const bf16x8*>(Kn + KNSWZ(32 + r32, cb));
;         p0 = __builtin_amdgcn_mfma_f32_32x32x16_bf16(b0, qr[d0], p0, 0, 0, 0);
;         p1 = __builtin_amdgcn_mfma_f32_32x32x16_bf16(b1, qr[d0], p1, 0, 0, 0); }
; #pragma unroll
;     for (int d0 = 0; d0 < 4; ++d0) { const int cb = (d0 * 16 + hi * 8) * 2;
;         const bf16x8 b0 = *reinterpret_cast<const bf16x8*>(Kr + KRSWZ(r32, cb));
;         const bf16x8 b1 = *reinterpret_cast<const bf16x8*>(Kr + KRSWZ(32 + r32, cb));
;         p0 = __builtin_amdgcn_mfma_f32_32x32x16_bf16(b0, qr[8 + d0], p0, 0, 0, 0);
;         p1 = __builtin_amdgcn_mfma_f32_32x32x16_bf16(b1, qr[8 + d0], p1, 0, 0, 0); }
; }
	v_mov_b32_e32 v184, v182
	v_mov_b32_e32 v233, 1.0
	s_cmp_lg_u32 s19, 0
	s_cbranch_scc0 .LBB0_228
.LBB0_221:
	v_exp_f32_e32 v182, v98
	v_exp_f32_e32 v172, v96
	v_exp_f32_e32 v173, v97
	v_exp_f32_e32 v195, v99
	v_exp_f32_e32 v196, v100
	v_exp_f32_e32 v197, v101
	v_exp_f32_e32 v198, v102
	v_exp_f32_e32 v199, v103
	v_exp_f32_e32 v200, v104
	v_exp_f32_e32 v234, v105
	v_exp_f32_e32 v235, v106
	v_exp_f32_e32 v236, v107
	v_exp_f32_e32 v237, v108
	v_exp_f32_e32 v238, v109
	v_exp_f32_e32 v239, v110
	v_exp_f32_e32 v240, v111
	s_mul_i32 s0, s10, 0x6000
	s_add_i32 s16, s0, 0
	s_add_i32 s17, s16, s6
	s_add_i32 s18, s16, s8
	s_waitcnt vmcnt(0) lgkmcnt(0)
	s_barrier
	s_add_i32 s15, s7, s15
	s_setprio 1
	v_add_u32_e32 v68, s14, v207
	ds_read_b128 v[64:67], v68
	ds_read_b128 v[68:71], v68 offset:8192
	v_add_u32_e32 v186, s14, v210
	ds_read_b128 v[168:171], v186
	ds_read_b128 v[186:189], v186 offset:8192
	s_waitcnt lgkmcnt(0)
	v_mfma_f32_32x32x16_bf16 v[96:111], v[64:67], v[156:159], 0
	v_mfma_f32_32x32x16_bf16 v[64:79], v[68:71], v[156:159], 0
	v_mfma_f32_32x32x16_bf16 v[96:111], v[168:171], v[152:155], v[96:111]
	v_mfma_f32_32x32x16_bf16 v[64:79], v[186:189], v[152:155], v[64:79]
	v_add_u32_e32 v186, s14, v218
	ds_read_b128 v[168:171], v186
	ds_read_b128 v[186:189], v186 offset:8192
	s_mov_b32 m0, s17
	s_add_u32 s100, s72, 0x26580000
	s_addc_u32 s101, s73, 0
	global_load_lds_dwordx4 v178, s[100:101]
	s_waitcnt lgkmcnt(0)
	v_mfma_f32_32x32x16_bf16 v[96:111], v[168:171], v[148:151], v[96:111]
	v_mfma_f32_32x32x16_bf16 v[64:79], v[186:189], v[148:151], v[64:79]
	v_add_u32_e32 v186, s14, v221
	ds_read_b128 v[168:171], v186
	ds_read_b128 v[186:189], v186 offset:8192
	s_waitcnt lgkmcnt(0)
	v_mfma_f32_32x32x16_bf16 v[96:111], v[168:171], v[144:147], v[96:111]
	v_mfma_f32_32x32x16_bf16 v[64:79], v[186:189], v[144:147], v[64:79]
	v_add_u32_e32 v186, s14, v222
	ds_read_b128 v[168:171], v186
	ds_read_b128 v[186:189], v186 offset:8192
	s_add_i32 m0, s17, 0x400
	s_nop 0
	global_load_lds_dwordx4 v180, s[100:101]
	v_exp_f32_e32 v190, v88
	s_waitcnt lgkmcnt(0)
	v_mfma_f32_32x32x16_bf16 v[96:111], v[168:171], v[140:143], v[96:111]
	v_mfma_f32_32x32x16_bf16 v[64:79], v[186:189], v[140:143], v[64:79]
	v_add_u32_e32 v186, s14, v223
	ds_read_b128 v[168:171], v186
	ds_read_b128 v[186:189], v186 offset:8192
	v_exp_f32_e32 v191, v89
	s_waitcnt lgkmcnt(0)
	v_mfma_f32_32x32x16_bf16 v[96:111], v[168:171], v[136:139], v[96:111]
	v_mfma_f32_32x32x16_bf16 v[64:79], v[186:189], v[136:139], v[64:79]
	v_add_u32_e32 v186, s14, v224
	ds_read_b128 v[168:171], v186
	ds_read_b128 v[186:189], v186 offset:8192
	s_mov_b32 m0, s15
	s_add_u32 s100, s72, 0x26580100
	s_addc_u32 s101, s73, 0
	global_load_lds_dwordx4 v176, s[100:101]
	v_exp_f32_e32 v192, v90
	s_waitcnt lgkmcnt(0)
	v_mfma_f32_32x32x16_bf16 v[96:111], v[168:171], v[132:135], v[96:111]
	v_mfma_f32_32x32x16_bf16 v[64:79], v[186:189], v[132:135], v[64:79]
	v_add_u32_e32 v186, s14, v225
	ds_read_b128 v[168:171], v186
	ds_read_b128 v[186:189], v186 offset:8192
	v_exp_f32_e32 v193, v91
	s_waitcnt lgkmcnt(0)
	v_mfma_f32_32x32x16_bf16 v[96:111], v[168:171], v[128:131], v[96:111]
	v_mfma_f32_32x32x16_bf16 v[64:79], v[186:189], v[128:131], v[64:79]
	v_add_u32_e32 v186, s14, v226
	ds_read_b128 v[168:171], v186 offset:16384
	ds_read_b128 v[186:189], v186 offset:20480
	s_add_i32 m0, s15, 0x400
	s_add_u32 s100, s72, 0x26580180
	s_addc_u32 s101, s73, 0
	global_load_lds_dwordx4 v176, s[100:101]
	v_exp_f32_e32 v241, v92
	s_waitcnt lgkmcnt(0)
	v_mfma_f32_32x32x16_bf16 v[96:111], v[168:171], v[124:127], v[96:111]
	v_mfma_f32_32x32x16_bf16 v[64:79], v[186:189], v[124:127], v[64:79]
	v_add_u32_e32 v186, s14, v227
	ds_read_b128 v[168:171], v186 offset:16384
	ds_read_b128 v[186:189], v186 offset:20480
	v_exp_f32_e32 v242, v93
	s_waitcnt lgkmcnt(0)
	v_mfma_f32_32x32x16_bf16 v[96:111], v[168:171], v[120:123], v[96:111]
	v_mfma_f32_32x32x16_bf16 v[64:79], v[186:189], v[120:123], v[64:79]
	v_add_u32_e32 v186, s14, v228
	ds_read_b128 v[168:171], v186 offset:16384
	ds_read_b128 v[186:189], v186 offset:20480
	s_add_i32 m0, s18, 0x4000
	s_add_u32 s100, s72, 0x21206000
	s_addc_u32 s101, s73, 0
	global_load_lds_dwordx4 v174, s[100:101]
	v_exp_f32_e32 v94, v94
	s_waitcnt lgkmcnt(0)
	v_mfma_f32_32x32x16_bf16 v[96:111], v[168:171], v[116:119], v[96:111]
	v_mfma_f32_32x32x16_bf16 v[64:79], v[186:189], v[116:119], v[64:79]
	v_add_u32_e32 v186, s14, v229
	ds_read_b128 v[168:171], v186 offset:16384
	ds_read_b128 v[186:189], v186 offset:20480
	v_exp_f32_e32 v95, v95
	s_waitcnt lgkmcnt(0)
; __device__ __forceinline__ void finishSM(f32x16& p0, f32x16& p1, float alpha, float& l_reg, bf16x8& pa0, bf16x8& pa1, bf16x8& pa2, bf16x8& pa3) {
; #pragma unroll
;     for (int r = 0; r < 16; ++r) p1[r] = __builtin_amdgcn_exp2f(p1[r]);
;     float ps = 0;
; #pragma unroll
;     for (int r = 0; r < 16; ++r) ps += p0[r];
; #pragma unroll
;     for (int r = 0; r < 16; ++r) ps += p1[r];
;     { auto rr = __builtin_amdgcn_permlane32_swap(__float_as_uint(ps), __float_as_uint(ps), false, false);
;       ps = __uint_as_float(rr[0]) + __uint_as_float(rr[1]); }
;     l_reg = l_reg * alpha + ps;
;     ...
;     PK4(p0, 0, pa0); PK4(p0, 8, pa1); PK4(p1, 0, pa2); PK4(p1, 8, pa3);
;     ...
; }
; __device__ __forceinline__ void qkt(f32x16& p0, f32x16& p1, const char* Kn, const bf16x8* qr, int r32, int hi) {
;     const char* Kr = Kn + KR_OFF;
;     p0 = f32x16{}; p1 = f32x16{};
;     __builtin_amdgcn_s_setprio(1);
; #pragma unroll
;     for (int d0 = 0; d0 < 8; ++d0) { const int cb = (d0 * 16 + hi * 8) * 2;
;         const bf16x8 b0 = *reinterpret_cast<const bf16x8*>(Kn + KNSWZ(r32, cb));
;         const bf16x8 b1 = *reinterpret_cast<const bf16x8*>(Kn + KNSWZ(32 + r32, cb));
;         p0 = __builtin_amdgcn_mfma_f32_32x32x16_bf16(b0, qr[d0], p0, 0, 0, 0);
;         p1 = __builtin_amdgcn_mfma_f32_32x32x16_bf16(b1, qr[d0], p1, 0, 0, 0); }
; #pragma unroll
;     for (int d0 = 0; d0 < 4; ++d0) { const int cb = (d0 * 16 + hi * 8) * 2;
;         const bf16x8 b0 = *reinterpret_cast<const bf16x8*>(Kr + KRSWZ(r32, cb));
;         const bf16x8 b1 = *reinterpret_cast<const bf16x8*>(Kr + KRSWZ(32 + r32, cb));
;         p0 = __builtin_amdgcn_mfma_f32_32x32x16_bf16(b0, qr[8 + d0], p0, 0, 0, 0);
;         p1 = __builtin_amdgcn_mfma_f32_32x32x16_bf16(b1, qr[8 + d0], p1, 0, 0, 0); }
; }
; __device__ __forceinline__ int v_st(int k, int c) { const int kk = (k & ~0xC) | ((k & 4) << 1) | ((k & 8) >> 1); return ((kk >> 3) * 4 + (c >> 5)) * 512 + ((kk & 7) * 32 + (c & 31)) * 2; }
; __device__ __forceinline__ int v_rd_base(int lane) { return ((lane & 3) << 3) | (((lane >> 2) & 3) << 6) | (((lane >> 4) & 1) << 5) | (((lane >> 5) & 1) << 8); }
; template <int OFF> __device__ __forceinline__ s16x4 tr_read(int vb) {
;     s16x4 r; asm volatile("ds_read_b64_tr_b16 %0, %1 offset:%2" : "=&v"(r) : "v"(vb), "i"(OFF) : "memory"); return r;
; }
	v_mfma_f32_32x32x16_bf16 v[96:111], v[168:171], v[112:115], v[96:111]
	v_exp_f32_e32 v168, v80
	v_add_f32_e32 v80, 0, v172
	v_add_f32_e32 v80, v173, v80
	v_add_f32_e32 v80, v182, v80
	v_add_f32_e32 v80, v195, v80
	v_add_f32_e32 v80, v196, v80
	v_add_f32_e32 v80, v197, v80
	v_add_f32_e32 v80, v198, v80
	v_add_f32_e32 v80, v199, v80
	v_add_f32_e32 v80, v200, v80
	v_add_f32_e32 v80, v234, v80
	v_add_f32_e32 v80, v235, v80
	v_add_f32_e32 v80, v236, v80
	v_add_f32_e32 v80, v237, v80
	v_exp_f32_e32 v169, v81
	v_add_f32_e32 v80, v238, v80
	v_exp_f32_e32 v170, v82
	v_add_f32_e32 v80, v239, v80
	v_exp_f32_e32 v171, v83
	v_add_f32_e32 v80, v240, v80
	v_mfma_f32_32x32x16_bf16 v[64:79], v[186:189], v[112:115], v[64:79]
	v_exp_f32_e32 v186, v84
	v_add_f32_e32 v80, v168, v80
	v_exp_f32_e32 v187, v85
	v_add_f32_e32 v80, v169, v80
	v_exp_f32_e32 v188, v86
	v_add_f32_e32 v80, v170, v80
	v_exp_f32_e32 v189, v87
	v_add_f32_e32 v80, v171, v80
	v_add_f32_e32 v80, v186, v80
	v_add_f32_e32 v80, v187, v80
	v_add_f32_e32 v80, v188, v80
	v_add_f32_e32 v80, v189, v80
	v_add_f32_e32 v80, v190, v80
	v_add_f32_e32 v80, v191, v80
	v_add_f32_e32 v80, v192, v80
	v_add_f32_e32 v80, v193, v80
	v_add_f32_e32 v80, v241, v80
	v_add_f32_e32 v80, v242, v80
	v_add_f32_e32 v80, v94, v80
	v_add_f32_e32 v80, v95, v80
	v_mov_b32_e32 v81, v80
	v_cvt_pk_bf16_f32 v82, v172, v173
	v_cvt_pk_bf16_f32 v83, v182, v195
	v_cvt_pk_bf16_f32 v84, v196, v197
	s_nop 1
	v_permlane32_swap_b32_e32 v80, v81
	v_cvt_pk_bf16_f32 v85, v198, v199
	v_permlane32_swap_b32_e32 v82, v84
	v_cvt_pk_bf16_f32 v86, v200, v234
	v_cvt_pk_bf16_f32 v87, v235, v236
	v_cvt_pk_bf16_f32 v88, v237, v238
	v_cvt_pk_bf16_f32 v89, v239, v240
	v_cvt_pk_bf16_f32 v90, v168, v169
	v_cvt_pk_bf16_f32 v91, v170, v171
	v_cvt_pk_bf16_f32 v92, v186, v187
	v_cvt_pk_bf16_f32 v93, v188, v189
	v_cvt_pk_bf16_f32 v168, v190, v191
	v_cvt_pk_bf16_f32 v169, v192, v193
	v_cvt_pk_bf16_f32 v170, v241, v242
	v_cvt_pk_bf16_f32 v171, v94, v95
	v_permlane32_swap_b32_e32 v83, v85
	v_permlane32_swap_b32_e32 v86, v88
	v_permlane32_swap_b32_e32 v87, v89
	v_permlane32_swap_b32_e32 v90, v92
	v_permlane32_swap_b32_e32 v91, v93
	v_permlane32_swap_b32_e32 v168, v170
	v_permlane32_swap_b32_e32 v169, v171
	s_setprio 0
	v_lshl_add_u32 v94, s13, 14, v205
	ds_read_b64_tr_b16 v[186:187], v94 offset:0
	ds_read_b64_tr_b16 v[188:189], v94 offset:0x800
	ds_read_b64_tr_b16 v[190:191], v94 offset:0x1000
	ds_read_b64_tr_b16 v[192:193], v94 offset:0x1800
	ds_read_b64_tr_b16 v[196:197], v94 offset:0x2000
	ds_read_b64_tr_b16 v[198:199], v94 offset:0x2800
	ds_read_b64_tr_b16 v[234:235], v94 offset:0x3000
	ds_read_b64_tr_b16 v[236:237], v94 offset:0x3800
	s_waitcnt lgkmcnt(0)
	s_nop 0
	v_mfma_f32_32x32x16_bf16 v[0:15], v[82:85], v[186:189], v[0:15]
	ds_read_b64_tr_b16 v[186:187], v94 offset:0x200
	ds_read_b64_tr_b16 v[188:189], v94 offset:0xa00
	v_mfma_f32_32x32x16_bf16 v[0:15], v[86:89], v[190:193], v[0:15]
	ds_read_b64_tr_b16 v[190:191], v94 offset:0x1200
	ds_read_b64_tr_b16 v[192:193], v94 offset:0x1a00
	v_mfma_f32_32x32x16_bf16 v[0:15], v[90:93], v[196:199], v[0:15]
	ds_read_b64_tr_b16 v[196:197], v94 offset:0x2200
	ds_read_b64_tr_b16 v[198:199], v94 offset:0x2a00
	v_mfma_f32_32x32x16_bf16 v[0:15], v[168:171], v[234:237], v[0:15]
	ds_read_b64_tr_b16 v[234:235], v94 offset:0x3200
	ds_read_b64_tr_b16 v[236:237], v94 offset:0x3a00
	s_waitcnt lgkmcnt(0)
	v_mfma_f32_32x32x16_bf16 v[48:63], v[82:85], v[186:189], v[48:63]
	ds_read_b64_tr_b16 v[186:187], v94 offset:0x400
	ds_read_b64_tr_b16 v[188:189], v94 offset:0xc00
	v_mfma_f32_32x32x16_bf16 v[48:63], v[86:89], v[190:193], v[48:63]
	ds_read_b64_tr_b16 v[190:191], v94 offset:0x1400
	ds_read_b64_tr_b16 v[192:193], v94 offset:0x1c00
	v_mfma_f32_32x32x16_bf16 v[48:63], v[90:93], v[196:199], v[48:63]
	ds_read_b64_tr_b16 v[196:197], v94 offset:0x2400
	ds_read_b64_tr_b16 v[198:199], v94 offset:0x2c00
	v_mfma_f32_32x32x16_bf16 v[48:63], v[168:171], v[234:237], v[48:63]
	ds_read_b64_tr_b16 v[234:235], v94 offset:0x3400
	ds_read_b64_tr_b16 v[236:237], v94 offset:0x3c00
	s_waitcnt lgkmcnt(0)
	v_mfma_f32_32x32x16_bf16 v[32:47], v[82:85], v[186:189], v[32:47]
	ds_read_b64_tr_b16 v[186:187], v94 offset:0x600
	ds_read_b64_tr_b16 v[188:189], v94 offset:0xe00
	v_mfma_f32_32x32x16_bf16 v[32:47], v[86:89], v[190:193], v[32:47]
	ds_read_b64_tr_b16 v[190:191], v94 offset:0x1600
	ds_read_b64_tr_b16 v[192:193], v94 offset:0x1e00
	v_mfma_f32_32x32x16_bf16 v[32:47], v[90:93], v[196:199], v[32:47]
	ds_read_b64_tr_b16 v[196:197], v94 offset:0x2600
	ds_read_b64_tr_b16 v[198:199], v94 offset:0x2e00
	v_mfma_f32_32x32x16_bf16 v[32:47], v[168:171], v[234:237], v[32:47]
	ds_read_b64_tr_b16 v[234:235], v94 offset:0x3600
	ds_read_b64_tr_b16 v[236:237], v94 offset:0x3e00
	s_waitcnt lgkmcnt(0)
	v_mfma_f32_32x32x16_bf16 v[16:31], v[82:85], v[186:189], v[16:31]
	v_max_f32_e32 v82, v97, v97
	v_max_f32_e32 v83, v96, v96
	v_max_f32_e32 v82, v83, v82
	v_max3_f32 v82, v82, v98, v99
	v_max3_f32 v82, v82, v100, v101
	v_max3_f32 v82, v82, v102, v103
	v_max3_f32 v82, v82, v104, v105
	v_mfma_f32_32x32x16_bf16 v[16:31], v[86:89], v[190:193], v[16:31]
	v_max3_f32 v82, v82, v106, v107
	v_max3_f32 v82, v82, v108, v109
	v_max3_f32 v82, v82, v110, v111
	v_max3_f32 v82, v82, v64, v65
	v_max3_f32 v82, v82, v66, v67
	v_max3_f32 v82, v82, v68, v69
	v_max3_f32 v82, v82, v70, v71
	v_mfma_f32_32x32x16_bf16 v[16:31], v[90:93], v[196:199], v[16:31]
	v_max3_f32 v82, v82, v72, v73
	v_max3_f32 v82, v82, v74, v75
	v_max3_f32 v82, v82, v76, v77
	v_max3_f32 v82, v82, v78, v79
	v_mov_b32_e32 v83, v82
	s_nop 1
	v_permlane32_swap_b32_e32 v82, v83
	v_max_f32_e32 v83, v83, v83
	v_max_f32_e32 v82, v82, v82
	v_mfma_f32_32x32x16_bf16 v[16:31], v[168:171], v[234:237], v[16:31]
	v_max_f32_e32 v82, v82, v83
	v_sub_f32_e32 v83, v82, v184
	s_mov_b32 s0, 0x41300000
	v_cmp_ge_f32_e32 vcc, s0, v83
	s_cmp_eq_u64 vcc, exec
	s_cbranch_scc0 .Latt_slow2
	v_mov_b32_e32 v182, v184
	s_cmp_lg_u32 s19, 0
	s_cbranch_scc0 .LBB0_229
	v_mov_b32_e32 v184, 1.0

; template <bool FIRST>
; __device__ __forceinline__ void partialSM(f32x16& p0, f32x16& p1, float& m_reg, float& mn, float& alpha) {
;     ...
;     else { mn = fmaxf(m_reg, pmax); alpha = __builtin_amdgcn_exp2f(m_reg - mn); m_reg = mn; }
;     if (!__builtin_expect(__all(mn == 0.f), 1)) {
.Latt_slow1:
	v_max_f32_e32 v65, v182, v182
	s_cselect_b64 vcc, -1, 0
	v_max_f32_e32 v64, v65, v64
	v_cndmask_b32_e32 v184, v64, v182, vcc
	v_cmp_eq_f32_e64 s[0:1], 0, v184
	s_cmp_eq_u64 s[0:1], exec
	s_cselect_b32 s19, 1, 0
	s_cbranch_scc0 .LBB0_228

; template <bool FIRST>
; __device__ __forceinline__ void partialSM(f32x16& p0, f32x16& p1, float& m_reg, float& mn, float& alpha) {
;     ...
;     else { mn = fmaxf(m_reg, pmax); alpha = __builtin_amdgcn_exp2f(m_reg - mn); m_reg = mn; }
;     if (!__builtin_expect(__all(mn == 0.f), 1)) {
.Latt_slow2:
	v_max_f32_e32 v83, v184, v184
	s_cselect_b64 vcc, -1, 0
	v_max_f32_e32 v82, v83, v82
	v_cndmask_b32_e32 v182, v82, v184, vcc
	v_cmp_eq_f32_e64 s[0:1], 0, v182
	s_cmp_eq_u64 s[0:1], exec
	s_cselect_b32 s19, 1, 0
	s_cbranch_scc0 .LBB0_229
